# RWKV prompt loop: next-chunk loads and gate LoRA block laid out in line (fewer taken branches per iteration); code placement +56 bytes
# speedup vs baseline: 1.0167x; 1.0045x over previous
.LBB0_1228:
	s_or_b64 exec, exec, s[14:15]
	v_and_b32_e32 v59, 63, v56
	v_lshrrev_b32_e32 v60, 3, v59
	v_ashrrev_i32_e32 v59, 5, v56
	v_and_b32_e32 v93, 7, v56
	v_lshl_add_u32 v56, v63, 2, 0
	v_lshlrev_b32_e32 v63, 1, v63
	v_lshl_add_u32 v61, v67, 2, v56
	v_sub_u32_e32 v56, v56, v63
	v_lshlrev_b32_e32 v63, 1, v67
	v_lshlrev_b32_e32 v71, 8, v62
	v_lshlrev_b32_e32 v62, 7, v62
	v_lshlrev_b32_e32 v67, 2, v66
	v_add3_u32 v109, v56, v63, v62
	s_movk_i32 s24, 0x710
	v_lshl_or_b32 v63, v59, 6, v66
	v_add_u32_e32 v68, 0, v67
	v_mul_lo_u32 v56, v59, s24
	v_lshlrev_b32_e32 v66, 2, v63
	v_lshl_or_b32 v108, v57, 3, v60
	v_mov_b32_e32 v77, 0
	v_lshlrev_b32_e32 v69, 2, v65
	v_add_u32_e32 v62, 0, v56
	v_add_u32_e32 v92, 0, v66
	v_add_u32_e32 v111, v68, v56
	v_and_b32_e32 v56, 32, v174
	s_add_i32 s16, 0, 0x16200
	s_movk_i32 s17, 0xf8f4
	v_lshl_add_u64 v[90:91], s[12:13], 0, v[76:77]
	v_sub_u32_e32 v69, v68, v69
	v_cmp_eq_u32_e64 s[12:13], 0, v56
	v_add_u32_e32 v112, s16, v66
	v_mul_lo_u32 v56, v59, s17
	v_lshl_add_u32 v115, v108, 2, s16
	v_mad_u64_u32 v[94:95], s[16:17], v63, 28, v[92:93]
	v_lshl_add_u32 v113, v59, 7, v69
	v_cmp_gt_i32_e64 s[16:17], 16, v59
	v_add_u32_e32 v95, s3, v59
	v_mul_lo_u32 v59, v89, s24
	v_add_u32_e32 v66, 0, v59
	v_mov_b32_e32 v59, 0x1540
	v_mov_b32_e32 v68, s29
	v_cmp_gt_u32_e32 vcc, 24, v58
	v_add_u32_e32 v110, v62, v67
	v_lshlrev_b32_e32 v67, 5, v58
	v_cndmask_b32_e32 v59, v59, v68, vcc
	v_mov_b32_e32 v68, s28
	v_cmp_gt_u32_e32 vcc, 16, v58
	v_lshlrev_b32_e32 v70, 2, v93
	s_movk_i32 s25, 0xffe4
	v_cndmask_b32_e32 v59, v59, v68, vcc
	v_mov_b32_e32 v68, s5
	v_cmp_gt_i32_e32 vcc, 8, v58
	v_cmp_eq_u32_e64 s[14:15], 0, v65
	v_mul_u32_u24_e32 v65, 12, v93
	v_cndmask_b32_e32 v59, v59, v68, vcc
	v_lshl_add_u32 v58, v58, 3, v59
	v_ashrrev_i32_e32 v59, 31, v58
	v_lshl_add_u64 v[96:97], v[58:59], 1, s[22:23]
	v_mov_b32_e32 v58, 0x140
	v_cndmask_b32_e64 v76, v58, 64, s[18:19]
	v_mov_b32_e32 v58, 0x180
	v_mov_b32_e32 v59, 0x80
	v_cndmask_b32_e64 v98, v58, v59, s[18:19]
	v_mov_b32_e32 v58, 0x1c0
	v_mov_b32_e32 v59, 0xc0
	v_cndmask_b32_e64 v100, v58, v59, s[18:19]
	v_mov_b32_e32 v58, 0x100
	v_cndmask_b32_e64 v102, v58, 0, s[18:19]
	v_lshlrev_b32_e32 v58, 1, v64
	v_mov_b32_e32 v59, v77
	v_lshl_add_u64 v[106:107], s[20:21], 0, v[58:59]
	v_lshlrev_b32_e32 v58, 8, v57
	v_lshlrev_b32_e32 v59, 5, v60
	v_or3_b32 v58, v58, v59, v70
	v_mul_lo_u32 v63, v63, s25
	v_add_u32_e32 v116, 0xe200, v58
	s_movk_i32 s5, 0x7180
	v_lshlrev_b32_e32 v58, 2, v60
	s_mov_b32 s4, 0
	v_add3_u32 v114, 0, v70, v65
	v_mov_b32_e32 v99, v77
	v_mov_b32_e32 v101, v77
	v_mov_b32_e32 v103, v77
	s_waitcnt vmcnt(5)
	v_mov_b32_e32 v104, v85
	v_add3_u32 v117, v65, v70, s5
	v_lshl_or_b32 v118, v57, 5, v58
	v_add_u32_e32 v119, v66, v67
	s_movk_i32 s5, 0x800
	s_movk_i32 s28, 0x2e00
	s_mov_b32 s29, 0x800000
	v_mov_b32_e32 v120, 0x3a27c5ac
	v_add_u32_e32 v121, v94, v63
	v_add_u32_e32 v122, v61, v71
	v_add_u32_e32 v123, v62, v56
	v_mov_b32_e32 v127, v77
	v_mov_b32_e32 v126, v77
	v_mov_b32_e32 v125, v77
	v_mov_b32_e32 v124, v77
	s_nop 0
	s_nop 0
	s_nop 0
	s_nop 0
	s_nop 0
	s_nop 0
	s_nop 0
	s_nop 0
	s_nop 0
	s_nop 0
	s_nop 0
	s_nop 0
	s_nop 0
	s_nop 0
	s_nop 0
	s_nop 0
	s_nop 0
	s_nop 0
	s_mov_b32 s100, 0
	s_and_saveexec_b64 s[18:19], s[10:11]
	s_cbranch_execz .LBB0_1230

.LBB0_1230:
	s_or_b64 exec, exec, s[18:19]
	s_add_i32 s30, s4, 1
	s_cmpk_lg_i32 s4, 0x7f
	s_cselect_b64 s[18:19], -1, 0
	s_cmpk_eq_i32 s4, 0x7f
	s_cselect_b64 vcc, -1, 0
	s_waitcnt vmcnt(0)
	v_cndmask_b32_e32 v48, 0, v48, vcc
	s_nor_b64 s[24:25], s[8:9], vcc
	v_cndmask_b32_e32 v49, 0, v49, vcc
	v_cndmask_b32_e32 v50, 0, v50, vcc
	v_cndmask_b32_e32 v51, 0, v51, vcc
	v_cndmask_b32_e32 v52, 0, v52, vcc
	v_cndmask_b32_e32 v53, 0, v53, vcc
	v_cndmask_b32_e32 v54, 0, v54, vcc
	v_cndmask_b32_e32 v55, 0, v55, vcc
	s_and_saveexec_b64 s[22:23], s[24:25]
	s_cbranch_execz .Lrw_noload
	v_lshl_add_u32 v56, s30, 4, v89
	v_cmp_gt_i32_e32 vcc, s5, v56
	v_mov_b32_e32 v55, 0
	v_mov_b32_e32 v54, 0
	v_mov_b32_e32 v53, 0
	v_mov_b32_e32 v52, 0
	v_mov_b32_e32 v51, 0
	v_mov_b32_e32 v50, 0
	v_mov_b32_e32 v49, 0
	v_mov_b32_e32 v48, 0
	s_and_saveexec_b64 s[24:25], vcc
	s_cbranch_execz .LBB0_1248
	v_add_u32_e32 v57, s3, v56
	v_mad_i64_i32 v[48:49], s[26:27], v57, s28, v[96:97]
	global_load_dwordx4 v[48:51], v[48:49], off
	v_mov_b32_e32 v55, 0
	v_cmp_lt_i32_e32 vcc, 0, v56
	v_mov_b32_e32 v54, 0
	v_mov_b32_e32 v53, 0
	v_mov_b32_e32 v52, 0
	s_and_saveexec_b64 s[26:27], vcc
	s_cbranch_execz .LBB0_1247
	v_add_u32_e32 v52, -1, v57
	v_mad_i64_i32 v[52:53], s[34:35], v52, s28, v[96:97]
	global_load_dwordx4 v[52:55], v[52:53], off

.Lrw_noload:
	s_or_b64 exec, exec, s[22:23]
	s_and_saveexec_b64 s[22:23], s[6:7]
	s_xor_b64 s[22:23], exec, s[22:23]
	s_cbranch_execz .LBB0_1232
	v_mfma_f32_16x16x32_bf16 v[56:59], v[0:3], v[32:35], 0
	v_mfma_f32_16x16x32_bf16 v[56:59], v[4:7], v[36:39], v[56:59]
	v_mfma_f32_16x16x32_bf16 v[56:59], v[8:11], v[40:43], v[56:59]
	v_mfma_f32_16x16x32_bf16 v[56:59], v[12:15], v[44:47], v[56:59]
	v_add_u32_e32 v164, s100, v122
	s_nop 7
	ds_write_b128 v164, v[56:59] offset:37120

.LBB0_1238:
	s_or_b64 exec, exec, s[18:19]
	s_waitcnt lgkmcnt(0)
	s_barrier
	s_cmp_lg_u32 s100, 0
	s_cselect_b32 s97, 0x800, 0
	v_add_u32_e32 v167, s97, v114
	ds_read_b128 v[72:75], v114 offset:41216
	ds_read_b128 v[68:71], v114 offset:45312
	ds_read_b128 v[64:67], v114 offset:49408
	ds_read_b128 v[56:59], v114 offset:53504
	ds_read_b128 v[60:63], v167 offset:28928
	ds_read_b32 v85, v115
	s_waitcnt lgkmcnt(0)
	v_dot2_f32_f16 v151, v127, v72, 0
	v_dot2_f32_f16 v151, v126, v73, v151
	v_dot2_f32_f16 v151, v125, v74, v151
	v_dot2_f32_f16 v151, v124, v75, v151
	ds_read_b128 v[134:137], v114 offset:41344
	ds_read_b128 v[138:141], v114 offset:45440
	ds_read_b128 v[142:145], v114 offset:49536
	v_add_f32_dpp v151, v151, v151 quad_perm:[1,0,3,2] row_mask:0xf bank_mask:0xf bound_ctrl:1
	ds_read_b128 v[130:133], v167 offset:29056
	ds_read_b128 v[146:149], v114 offset:53632
	v_add_f32_dpp v151, v151, v151 quad_perm:[2,3,0,1] row_mask:0xf bank_mask:0xf bound_ctrl:1
	ds_read_b32 v160, v115 offset:256
	s_nop 0
	v_add_f32_dpp v151, v151, v151 row_half_mirror row_mask:0xf bank_mask:0xf bound_ctrl:1
	v_cvt_pkrtz_f16_f32 v152, -v151, -v151
	v_pk_mul_f16 v153, v152, v68
	v_pk_mul_f16 v154, v152, v69
	v_pk_mul_f16 v155, v152, v70
	v_pk_mul_f16 v156, v152, v71
	v_pk_fma_f16 v153, v85, v64, v153
	v_pk_fma_f16 v154, v85, v65, v154
	v_pk_fma_f16 v155, v85, v66, v155
	v_pk_fma_f16 v156, v85, v67, v156
	v_pk_fma_f16 v127, v127, v60, v153
	v_pk_fma_f16 v126, v126, v61, v154
	v_pk_fma_f16 v125, v125, v62, v155
	v_pk_fma_f16 v124, v124, v63, v156
	v_dot2_f32_f16 v157, v127, v56, 0
	v_dot2_f32_f16 v157, v126, v57, v157
	v_dot2_f32_f16 v157, v125, v58, v157
	v_dot2_f32_f16 v157, v124, v59, v157
	s_waitcnt lgkmcnt(0)
	v_dot2_f32_f16 v151, v127, v134, 0
	v_dot2_f32_f16 v151, v126, v135, v151
	v_dot2_f32_f16 v151, v125, v136, v151
	v_dot2_f32_f16 v151, v124, v137, v151
	ds_read_b128 v[72:75], v114 offset:41472
	ds_read_b128 v[68:71], v114 offset:45568
	ds_read_b128 v[64:67], v114 offset:49664
	v_add_f32_dpp v151, v151, v151 quad_perm:[1,0,3,2] row_mask:0xf bank_mask:0xf bound_ctrl:1
	ds_read_b128 v[60:63], v167 offset:29184
	ds_read_b128 v[56:59], v114 offset:53760
	v_add_f32_dpp v151, v151, v151 quad_perm:[2,3,0,1] row_mask:0xf bank_mask:0xf bound_ctrl:1
	ds_read_b32 v85, v115 offset:512
	ds_write_b32 v116, v157 offset:0
	v_add_f32_dpp v151, v151, v151 row_half_mirror row_mask:0xf bank_mask:0xf bound_ctrl:1
	v_cvt_pkrtz_f16_f32 v152, -v151, -v151
	v_pk_mul_f16 v153, v152, v138
	v_pk_mul_f16 v154, v152, v139
	v_pk_mul_f16 v155, v152, v140
	v_pk_mul_f16 v156, v152, v141
	v_pk_fma_f16 v153, v160, v142, v153
	v_pk_fma_f16 v154, v160, v143, v154
	v_pk_fma_f16 v155, v160, v144, v155
	v_pk_fma_f16 v156, v160, v145, v156
	v_pk_fma_f16 v127, v127, v130, v153
	v_pk_fma_f16 v126, v126, v131, v154
	v_pk_fma_f16 v125, v125, v132, v155
	v_pk_fma_f16 v124, v124, v133, v156
	v_dot2_f32_f16 v158, v127, v146, 0
	v_dot2_f32_f16 v158, v126, v147, v158
	v_dot2_f32_f16 v158, v125, v148, v158
	v_dot2_f32_f16 v158, v124, v149, v158
	s_waitcnt lgkmcnt(0)
	v_dot2_f32_f16 v151, v127, v72, 0
	v_dot2_f32_f16 v151, v126, v73, v151
	v_dot2_f32_f16 v151, v125, v74, v151
	v_dot2_f32_f16 v151, v124, v75, v151
	ds_read_b128 v[134:137], v114 offset:41600
	ds_read_b128 v[138:141], v114 offset:45696
	ds_read_b128 v[142:145], v114 offset:49792
	v_add_f32_dpp v151, v151, v151 quad_perm:[1,0,3,2] row_mask:0xf bank_mask:0xf bound_ctrl:1
	ds_read_b128 v[130:133], v167 offset:29312
	ds_read_b128 v[146:149], v114 offset:53888
	v_add_f32_dpp v151, v151, v151 quad_perm:[2,3,0,1] row_mask:0xf bank_mask:0xf bound_ctrl:1
	ds_read_b32 v160, v115 offset:768
	ds_write_b32 v116, v158 offset:2048
	v_add_f32_dpp v151, v151, v151 row_half_mirror row_mask:0xf bank_mask:0xf bound_ctrl:1
	v_cvt_pkrtz_f16_f32 v152, -v151, -v151
	v_pk_mul_f16 v153, v152, v68
	v_pk_mul_f16 v154, v152, v69
	v_pk_mul_f16 v155, v152, v70
	v_pk_mul_f16 v156, v152, v71
	v_pk_fma_f16 v153, v85, v64, v153
	v_pk_fma_f16 v154, v85, v65, v154
	v_pk_fma_f16 v155, v85, v66, v155
	v_pk_fma_f16 v156, v85, v67, v156
	v_pk_fma_f16 v127, v127, v60, v153
	v_pk_fma_f16 v126, v126, v61, v154
	v_pk_fma_f16 v125, v125, v62, v155
	v_pk_fma_f16 v124, v124, v63, v156
	v_dot2_f32_f16 v157, v127, v56, 0
	v_dot2_f32_f16 v157, v126, v57, v157
	v_dot2_f32_f16 v157, v125, v58, v157
	v_dot2_f32_f16 v157, v124, v59, v157
	s_waitcnt lgkmcnt(0)
	v_dot2_f32_f16 v151, v127, v134, 0
	v_dot2_f32_f16 v151, v126, v135, v151
	v_dot2_f32_f16 v151, v125, v136, v151
	v_dot2_f32_f16 v151, v124, v137, v151
	ds_read_b128 v[72:75], v114 offset:41728
	ds_read_b128 v[68:71], v114 offset:45824
	ds_read_b128 v[64:67], v114 offset:49920
	v_add_f32_dpp v151, v151, v151 quad_perm:[1,0,3,2] row_mask:0xf bank_mask:0xf bound_ctrl:1
	ds_read_b128 v[60:63], v167 offset:29440
	ds_read_b128 v[56:59], v114 offset:54016
	v_add_f32_dpp v151, v151, v151 quad_perm:[2,3,0,1] row_mask:0xf bank_mask:0xf bound_ctrl:1
	ds_read_b32 v85, v115 offset:1024
	ds_write_b32 v116, v157 offset:4096
	v_add_f32_dpp v151, v151, v151 row_half_mirror row_mask:0xf bank_mask:0xf bound_ctrl:1
	v_cvt_pkrtz_f16_f32 v152, -v151, -v151
	v_pk_mul_f16 v153, v152, v138
	v_pk_mul_f16 v154, v152, v139
	v_pk_mul_f16 v155, v152, v140
	v_pk_mul_f16 v156, v152, v141
	v_pk_fma_f16 v153, v160, v142, v153
	v_pk_fma_f16 v154, v160, v143, v154
	v_pk_fma_f16 v155, v160, v144, v155
	v_pk_fma_f16 v156, v160, v145, v156
	v_pk_fma_f16 v127, v127, v130, v153
	v_pk_fma_f16 v126, v126, v131, v154
	v_pk_fma_f16 v125, v125, v132, v155
	v_pk_fma_f16 v124, v124, v133, v156
	v_dot2_f32_f16 v158, v127, v146, 0
	v_dot2_f32_f16 v158, v126, v147, v158
	v_dot2_f32_f16 v158, v125, v148, v158
	v_dot2_f32_f16 v158, v124, v149, v158
	s_waitcnt lgkmcnt(0)
	v_dot2_f32_f16 v151, v127, v72, 0
	v_dot2_f32_f16 v151, v126, v73, v151
	v_dot2_f32_f16 v151, v125, v74, v151
	v_dot2_f32_f16 v151, v124, v75, v151
	ds_read_b128 v[134:137], v114 offset:41856
	ds_read_b128 v[138:141], v114 offset:45952
	ds_read_b128 v[142:145], v114 offset:50048
	v_add_f32_dpp v151, v151, v151 quad_perm:[1,0,3,2] row_mask:0xf bank_mask:0xf bound_ctrl:1
	ds_read_b128 v[130:133], v167 offset:29568
	ds_read_b128 v[146:149], v114 offset:54144
	v_add_f32_dpp v151, v151, v151 quad_perm:[2,3,0,1] row_mask:0xf bank_mask:0xf bound_ctrl:1
	ds_read_b32 v160, v115 offset:1280
	ds_write_b32 v116, v158 offset:6144
	v_add_f32_dpp v151, v151, v151 row_half_mirror row_mask:0xf bank_mask:0xf bound_ctrl:1
	v_cvt_pkrtz_f16_f32 v152, -v151, -v151
	v_pk_mul_f16 v153, v152, v68
	v_pk_mul_f16 v154, v152, v69
	v_pk_mul_f16 v155, v152, v70
	v_pk_mul_f16 v156, v152, v71
	v_pk_fma_f16 v153, v85, v64, v153
	v_pk_fma_f16 v154, v85, v65, v154
	v_pk_fma_f16 v155, v85, v66, v155
	v_pk_fma_f16 v156, v85, v67, v156
	v_pk_fma_f16 v127, v127, v60, v153
	v_pk_fma_f16 v126, v126, v61, v154
	v_pk_fma_f16 v125, v125, v62, v155
	v_pk_fma_f16 v124, v124, v63, v156
	v_dot2_f32_f16 v157, v127, v56, 0
	v_dot2_f32_f16 v157, v126, v57, v157
	v_dot2_f32_f16 v157, v125, v58, v157
	v_dot2_f32_f16 v157, v124, v59, v157
	s_waitcnt lgkmcnt(0)
	v_dot2_f32_f16 v151, v127, v134, 0
	v_dot2_f32_f16 v151, v126, v135, v151
	v_dot2_f32_f16 v151, v125, v136, v151
	v_dot2_f32_f16 v151, v124, v137, v151
	ds_read_b128 v[72:75], v114 offset:41984
	ds_read_b128 v[68:71], v114 offset:46080
	ds_read_b128 v[64:67], v114 offset:50176
	v_add_f32_dpp v151, v151, v151 quad_perm:[1,0,3,2] row_mask:0xf bank_mask:0xf bound_ctrl:1
	ds_read_b128 v[60:63], v167 offset:29696
	ds_read_b128 v[56:59], v114 offset:54272
	v_add_f32_dpp v151, v151, v151 quad_perm:[2,3,0,1] row_mask:0xf bank_mask:0xf bound_ctrl:1
	ds_read_b32 v85, v115 offset:1536
	ds_write_b32 v116, v157 offset:8192
	v_add_f32_dpp v151, v151, v151 row_half_mirror row_mask:0xf bank_mask:0xf bound_ctrl:1
	v_cvt_pkrtz_f16_f32 v152, -v151, -v151
	v_pk_mul_f16 v153, v152, v138
	v_pk_mul_f16 v154, v152, v139
	v_pk_mul_f16 v155, v152, v140
	v_pk_mul_f16 v156, v152, v141
	v_pk_fma_f16 v153, v160, v142, v153
	v_pk_fma_f16 v154, v160, v143, v154
	v_pk_fma_f16 v155, v160, v144, v155
	v_pk_fma_f16 v156, v160, v145, v156
	v_pk_fma_f16 v127, v127, v130, v153
	v_pk_fma_f16 v126, v126, v131, v154
	v_pk_fma_f16 v125, v125, v132, v155
	v_pk_fma_f16 v124, v124, v133, v156
	v_dot2_f32_f16 v158, v127, v146, 0
	v_dot2_f32_f16 v158, v126, v147, v158
	v_dot2_f32_f16 v158, v125, v148, v158
	v_dot2_f32_f16 v158, v124, v149, v158
	s_waitcnt lgkmcnt(0)
	v_dot2_f32_f16 v151, v127, v72, 0
	v_dot2_f32_f16 v151, v126, v73, v151
	v_dot2_f32_f16 v151, v125, v74, v151
	v_dot2_f32_f16 v151, v124, v75, v151
	ds_read_b128 v[134:137], v114 offset:42112
	ds_read_b128 v[138:141], v114 offset:46208
	ds_read_b128 v[142:145], v114 offset:50304
	v_add_f32_dpp v151, v151, v151 quad_perm:[1,0,3,2] row_mask:0xf bank_mask:0xf bound_ctrl:1
	ds_read_b128 v[130:133], v167 offset:29824
	ds_read_b128 v[146:149], v114 offset:54400
	v_add_f32_dpp v151, v151, v151 quad_perm:[2,3,0,1] row_mask:0xf bank_mask:0xf bound_ctrl:1
	ds_read_b32 v160, v115 offset:1792
	ds_write_b32 v116, v158 offset:10240
	v_add_f32_dpp v151, v151, v151 row_half_mirror row_mask:0xf bank_mask:0xf bound_ctrl:1
	v_cvt_pkrtz_f16_f32 v152, -v151, -v151
	v_pk_mul_f16 v153, v152, v68
	v_pk_mul_f16 v154, v152, v69
	v_pk_mul_f16 v155, v152, v70
	v_pk_mul_f16 v156, v152, v71
	v_pk_fma_f16 v153, v85, v64, v153
	v_pk_fma_f16 v154, v85, v65, v154
	v_pk_fma_f16 v155, v85, v66, v155
	v_pk_fma_f16 v156, v85, v67, v156
	v_pk_fma_f16 v127, v127, v60, v153
	v_pk_fma_f16 v126, v126, v61, v154
	v_pk_fma_f16 v125, v125, v62, v155
	v_pk_fma_f16 v124, v124, v63, v156
	v_dot2_f32_f16 v157, v127, v56, 0
	v_dot2_f32_f16 v157, v126, v57, v157
	v_dot2_f32_f16 v157, v125, v58, v157
	v_dot2_f32_f16 v157, v124, v59, v157
	s_waitcnt lgkmcnt(0)
	v_dot2_f32_f16 v151, v127, v134, 0
	v_dot2_f32_f16 v151, v126, v135, v151
	v_dot2_f32_f16 v151, v125, v136, v151
	v_dot2_f32_f16 v151, v124, v137, v151
	ds_read_b128 v[72:75], v114 offset:42240
	ds_read_b128 v[68:71], v114 offset:46336
	ds_read_b128 v[64:67], v114 offset:50432
	v_add_f32_dpp v151, v151, v151 quad_perm:[1,0,3,2] row_mask:0xf bank_mask:0xf bound_ctrl:1
	ds_read_b128 v[60:63], v167 offset:29952
	ds_read_b128 v[56:59], v114 offset:54528
	v_add_f32_dpp v151, v151, v151 quad_perm:[2,3,0,1] row_mask:0xf bank_mask:0xf bound_ctrl:1
	ds_read_b32 v85, v115 offset:2048
	ds_write_b32 v116, v157 offset:12288
	v_add_f32_dpp v151, v151, v151 row_half_mirror row_mask:0xf bank_mask:0xf bound_ctrl:1
	v_cvt_pkrtz_f16_f32 v152, -v151, -v151
	v_pk_mul_f16 v153, v152, v138
	v_pk_mul_f16 v154, v152, v139
	v_pk_mul_f16 v155, v152, v140
	v_pk_mul_f16 v156, v152, v141
	v_pk_fma_f16 v153, v160, v142, v153
	v_pk_fma_f16 v154, v160, v143, v154
	v_pk_fma_f16 v155, v160, v144, v155
	v_pk_fma_f16 v156, v160, v145, v156
	v_pk_fma_f16 v127, v127, v130, v153
	v_pk_fma_f16 v126, v126, v131, v154
	v_pk_fma_f16 v125, v125, v132, v155
	v_pk_fma_f16 v124, v124, v133, v156
	v_dot2_f32_f16 v158, v127, v146, 0
	v_dot2_f32_f16 v158, v126, v147, v158
	v_dot2_f32_f16 v158, v125, v148, v158
	v_dot2_f32_f16 v158, v124, v149, v158
	s_waitcnt lgkmcnt(0)
	v_dot2_f32_f16 v151, v127, v72, 0
	v_dot2_f32_f16 v151, v126, v73, v151
	v_dot2_f32_f16 v151, v125, v74, v151
	v_dot2_f32_f16 v151, v124, v75, v151
	ds_read_b128 v[134:137], v114 offset:42368
	ds_read_b128 v[138:141], v114 offset:46464
	ds_read_b128 v[142:145], v114 offset:50560
	v_add_f32_dpp v151, v151, v151 quad_perm:[1,0,3,2] row_mask:0xf bank_mask:0xf bound_ctrl:1
	ds_read_b128 v[130:133], v167 offset:30080
	ds_read_b128 v[146:149], v114 offset:54656
	v_add_f32_dpp v151, v151, v151 quad_perm:[2,3,0,1] row_mask:0xf bank_mask:0xf bound_ctrl:1
	ds_read_b32 v160, v115 offset:2304
	ds_write_b32 v116, v158 offset:14336
	v_add_f32_dpp v151, v151, v151 row_half_mirror row_mask:0xf bank_mask:0xf bound_ctrl:1
	v_cvt_pkrtz_f16_f32 v152, -v151, -v151
	v_pk_mul_f16 v153, v152, v68
	v_pk_mul_f16 v154, v152, v69
	v_pk_mul_f16 v155, v152, v70
	v_pk_mul_f16 v156, v152, v71
	v_pk_fma_f16 v153, v85, v64, v153
	v_pk_fma_f16 v154, v85, v65, v154
	v_pk_fma_f16 v155, v85, v66, v155
	v_pk_fma_f16 v156, v85, v67, v156
	v_pk_fma_f16 v127, v127, v60, v153
	v_pk_fma_f16 v126, v126, v61, v154
	v_pk_fma_f16 v125, v125, v62, v155
	v_pk_fma_f16 v124, v124, v63, v156
	v_dot2_f32_f16 v157, v127, v56, 0
	v_dot2_f32_f16 v157, v126, v57, v157
	v_dot2_f32_f16 v157, v125, v58, v157
	v_dot2_f32_f16 v157, v124, v59, v157
	s_waitcnt lgkmcnt(0)
	v_dot2_f32_f16 v151, v127, v134, 0
	v_dot2_f32_f16 v151, v126, v135, v151
	v_dot2_f32_f16 v151, v125, v136, v151
	v_dot2_f32_f16 v151, v124, v137, v151
	ds_read_b128 v[72:75], v114 offset:42496
	ds_read_b128 v[68:71], v114 offset:46592
	ds_read_b128 v[64:67], v114 offset:50688
	v_add_f32_dpp v151, v151, v151 quad_perm:[1,0,3,2] row_mask:0xf bank_mask:0xf bound_ctrl:1
	ds_read_b128 v[60:63], v167 offset:30208
	ds_read_b128 v[56:59], v114 offset:54784
	v_add_f32_dpp v151, v151, v151 quad_perm:[2,3,0,1] row_mask:0xf bank_mask:0xf bound_ctrl:1
	ds_read_b32 v85, v115 offset:2560
	ds_write_b32 v116, v157 offset:16384
	v_add_f32_dpp v151, v151, v151 row_half_mirror row_mask:0xf bank_mask:0xf bound_ctrl:1
	v_cvt_pkrtz_f16_f32 v152, -v151, -v151
	v_pk_mul_f16 v153, v152, v138
	v_pk_mul_f16 v154, v152, v139
	v_pk_mul_f16 v155, v152, v140
	v_pk_mul_f16 v156, v152, v141
	v_pk_fma_f16 v153, v160, v142, v153
	v_pk_fma_f16 v154, v160, v143, v154
	v_pk_fma_f16 v155, v160, v144, v155
	v_pk_fma_f16 v156, v160, v145, v156
	v_pk_fma_f16 v127, v127, v130, v153
	v_pk_fma_f16 v126, v126, v131, v154
	v_pk_fma_f16 v125, v125, v132, v155
	v_pk_fma_f16 v124, v124, v133, v156
	v_dot2_f32_f16 v158, v127, v146, 0
	v_dot2_f32_f16 v158, v126, v147, v158
	v_dot2_f32_f16 v158, v125, v148, v158
	v_dot2_f32_f16 v158, v124, v149, v158
	s_waitcnt lgkmcnt(0)
	v_dot2_f32_f16 v151, v127, v72, 0
	v_dot2_f32_f16 v151, v126, v73, v151
	v_dot2_f32_f16 v151, v125, v74, v151
	v_dot2_f32_f16 v151, v124, v75, v151
	ds_read_b128 v[134:137], v114 offset:42624
	ds_read_b128 v[138:141], v114 offset:46720
	ds_read_b128 v[142:145], v114 offset:50816
	v_add_f32_dpp v151, v151, v151 quad_perm:[1,0,3,2] row_mask:0xf bank_mask:0xf bound_ctrl:1
	ds_read_b128 v[130:133], v167 offset:30336
	ds_read_b128 v[146:149], v114 offset:54912
	v_add_f32_dpp v151, v151, v151 quad_perm:[2,3,0,1] row_mask:0xf bank_mask:0xf bound_ctrl:1
	ds_read_b32 v160, v115 offset:2816
	ds_write_b32 v116, v158 offset:18432
	v_add_f32_dpp v151, v151, v151 row_half_mirror row_mask:0xf bank_mask:0xf bound_ctrl:1
	v_cvt_pkrtz_f16_f32 v152, -v151, -v151
	v_pk_mul_f16 v153, v152, v68
	v_pk_mul_f16 v154, v152, v69
	v_pk_mul_f16 v155, v152, v70
	v_pk_mul_f16 v156, v152, v71
	v_pk_fma_f16 v153, v85, v64, v153
	v_pk_fma_f16 v154, v85, v65, v154
	v_pk_fma_f16 v155, v85, v66, v155
	v_pk_fma_f16 v156, v85, v67, v156
	v_pk_fma_f16 v127, v127, v60, v153
	v_pk_fma_f16 v126, v126, v61, v154
	v_pk_fma_f16 v125, v125, v62, v155
	v_pk_fma_f16 v124, v124, v63, v156
	v_dot2_f32_f16 v157, v127, v56, 0
	v_dot2_f32_f16 v157, v126, v57, v157
	v_dot2_f32_f16 v157, v125, v58, v157
	v_dot2_f32_f16 v157, v124, v59, v157
	s_waitcnt lgkmcnt(0)
	v_dot2_f32_f16 v151, v127, v134, 0
	v_dot2_f32_f16 v151, v126, v135, v151
	v_dot2_f32_f16 v151, v125, v136, v151
	v_dot2_f32_f16 v151, v124, v137, v151
	ds_read_b128 v[72:75], v114 offset:42752
	ds_read_b128 v[68:71], v114 offset:46848
	ds_read_b128 v[64:67], v114 offset:50944
	v_add_f32_dpp v151, v151, v151 quad_perm:[1,0,3,2] row_mask:0xf bank_mask:0xf bound_ctrl:1
	ds_read_b128 v[60:63], v167 offset:30464
	ds_read_b128 v[56:59], v114 offset:55040
	v_add_f32_dpp v151, v151, v151 quad_perm:[2,3,0,1] row_mask:0xf bank_mask:0xf bound_ctrl:1
	ds_read_b32 v85, v115 offset:3072
	ds_write_b32 v116, v157 offset:20480
	v_add_f32_dpp v151, v151, v151 row_half_mirror row_mask:0xf bank_mask:0xf bound_ctrl:1
	v_cvt_pkrtz_f16_f32 v152, -v151, -v151
	v_pk_mul_f16 v153, v152, v138
	v_pk_mul_f16 v154, v152, v139
	v_pk_mul_f16 v155, v152, v140
	v_pk_mul_f16 v156, v152, v141
	v_pk_fma_f16 v153, v160, v142, v153
	v_pk_fma_f16 v154, v160, v143, v154
	v_pk_fma_f16 v155, v160, v144, v155
	v_pk_fma_f16 v156, v160, v145, v156
	v_pk_fma_f16 v127, v127, v130, v153
	v_pk_fma_f16 v126, v126, v131, v154
	v_pk_fma_f16 v125, v125, v132, v155
	v_pk_fma_f16 v124, v124, v133, v156
	v_dot2_f32_f16 v158, v127, v146, 0
	v_dot2_f32_f16 v158, v126, v147, v158
	v_dot2_f32_f16 v158, v125, v148, v158
	v_dot2_f32_f16 v158, v124, v149, v158
	s_waitcnt lgkmcnt(0)
	v_dot2_f32_f16 v151, v127, v72, 0
	v_dot2_f32_f16 v151, v126, v73, v151
	v_dot2_f32_f16 v151, v125, v74, v151
	v_dot2_f32_f16 v151, v124, v75, v151
	ds_read_b128 v[134:137], v114 offset:42880
	ds_read_b128 v[138:141], v114 offset:46976
	ds_read_b128 v[142:145], v114 offset:51072
	v_add_f32_dpp v151, v151, v151 quad_perm:[1,0,3,2] row_mask:0xf bank_mask:0xf bound_ctrl:1
	ds_read_b128 v[130:133], v167 offset:30592
	ds_read_b128 v[146:149], v114 offset:55168
	v_add_f32_dpp v151, v151, v151 quad_perm:[2,3,0,1] row_mask:0xf bank_mask:0xf bound_ctrl:1
	ds_read_b32 v160, v115 offset:3328
	ds_write_b32 v116, v158 offset:22528
	v_add_f32_dpp v151, v151, v151 row_half_mirror row_mask:0xf bank_mask:0xf bound_ctrl:1
	v_cvt_pkrtz_f16_f32 v152, -v151, -v151
	v_pk_mul_f16 v153, v152, v68
	v_pk_mul_f16 v154, v152, v69
	v_pk_mul_f16 v155, v152, v70
	v_pk_mul_f16 v156, v152, v71
	v_pk_fma_f16 v153, v85, v64, v153
	v_pk_fma_f16 v154, v85, v65, v154
	v_pk_fma_f16 v155, v85, v66, v155
	v_pk_fma_f16 v156, v85, v67, v156
	v_pk_fma_f16 v127, v127, v60, v153
	v_pk_fma_f16 v126, v126, v61, v154
	v_pk_fma_f16 v125, v125, v62, v155
	v_pk_fma_f16 v124, v124, v63, v156
	v_dot2_f32_f16 v157, v127, v56, 0
	v_dot2_f32_f16 v157, v126, v57, v157
	v_dot2_f32_f16 v157, v125, v58, v157
	v_dot2_f32_f16 v157, v124, v59, v157
	s_waitcnt lgkmcnt(0)
	v_dot2_f32_f16 v151, v127, v134, 0
	v_dot2_f32_f16 v151, v126, v135, v151
	v_dot2_f32_f16 v151, v125, v136, v151
	v_dot2_f32_f16 v151, v124, v137, v151
	ds_read_b128 v[72:75], v114 offset:43008
	ds_read_b128 v[68:71], v114 offset:47104
	ds_read_b128 v[64:67], v114 offset:51200
	v_add_f32_dpp v151, v151, v151 quad_perm:[1,0,3,2] row_mask:0xf bank_mask:0xf bound_ctrl:1
	ds_read_b128 v[60:63], v167 offset:30720
	ds_read_b128 v[56:59], v114 offset:55296
	v_add_f32_dpp v151, v151, v151 quad_perm:[2,3,0,1] row_mask:0xf bank_mask:0xf bound_ctrl:1
	ds_read_b32 v85, v115 offset:3584
	ds_write_b32 v116, v157 offset:24576
	v_add_f32_dpp v151, v151, v151 row_half_mirror row_mask:0xf bank_mask:0xf bound_ctrl:1
	v_cvt_pkrtz_f16_f32 v152, -v151, -v151
	v_pk_mul_f16 v153, v152, v138
	v_pk_mul_f16 v154, v152, v139
	v_pk_mul_f16 v155, v152, v140
	v_pk_mul_f16 v156, v152, v141
	v_pk_fma_f16 v153, v160, v142, v153
	v_pk_fma_f16 v154, v160, v143, v154
	v_pk_fma_f16 v155, v160, v144, v155
	v_pk_fma_f16 v156, v160, v145, v156
	v_pk_fma_f16 v127, v127, v130, v153
	v_pk_fma_f16 v126, v126, v131, v154
	v_pk_fma_f16 v125, v125, v132, v155
	v_pk_fma_f16 v124, v124, v133, v156
	v_dot2_f32_f16 v158, v127, v146, 0
	v_dot2_f32_f16 v158, v126, v147, v158
	v_dot2_f32_f16 v158, v125, v148, v158
	v_dot2_f32_f16 v158, v124, v149, v158
	s_waitcnt lgkmcnt(0)
	v_dot2_f32_f16 v151, v127, v72, 0
	v_dot2_f32_f16 v151, v126, v73, v151
	v_dot2_f32_f16 v151, v125, v74, v151
	v_dot2_f32_f16 v151, v124, v75, v151
	ds_read_b128 v[134:137], v114 offset:43136
	ds_read_b128 v[138:141], v114 offset:47232
	ds_read_b128 v[142:145], v114 offset:51328
	v_add_f32_dpp v151, v151, v151 quad_perm:[1,0,3,2] row_mask:0xf bank_mask:0xf bound_ctrl:1
	ds_read_b128 v[130:133], v167 offset:30848
	ds_read_b128 v[146:149], v114 offset:55424
	v_add_f32_dpp v151, v151, v151 quad_perm:[2,3,0,1] row_mask:0xf bank_mask:0xf bound_ctrl:1
	ds_read_b32 v160, v115 offset:3840
	ds_write_b32 v116, v158 offset:26624
	v_add_f32_dpp v151, v151, v151 row_half_mirror row_mask:0xf bank_mask:0xf bound_ctrl:1
	v_cvt_pkrtz_f16_f32 v152, -v151, -v151
	v_pk_mul_f16 v153, v152, v68
	v_pk_mul_f16 v154, v152, v69
	v_pk_mul_f16 v155, v152, v70
	v_pk_mul_f16 v156, v152, v71
	v_pk_fma_f16 v153, v85, v64, v153
	v_pk_fma_f16 v154, v85, v65, v154
	v_pk_fma_f16 v155, v85, v66, v155
	v_pk_fma_f16 v156, v85, v67, v156
	v_pk_fma_f16 v127, v127, v60, v153
	v_pk_fma_f16 v126, v126, v61, v154
	v_pk_fma_f16 v125, v125, v62, v155
	v_pk_fma_f16 v124, v124, v63, v156
	v_dot2_f32_f16 v157, v127, v56, 0
	v_dot2_f32_f16 v157, v126, v57, v157
	v_dot2_f32_f16 v157, v125, v58, v157
	v_dot2_f32_f16 v157, v124, v59, v157
	s_waitcnt lgkmcnt(0)
	v_dot2_f32_f16 v151, v127, v134, 0
	v_dot2_f32_f16 v151, v126, v135, v151
	v_dot2_f32_f16 v151, v125, v136, v151
	v_dot2_f32_f16 v151, v124, v137, v151
	s_nop 2
	v_add_f32_dpp v151, v151, v151 quad_perm:[1,0,3,2] row_mask:0xf bank_mask:0xf bound_ctrl:1
	s_nop 1
	v_add_f32_dpp v151, v151, v151 quad_perm:[2,3,0,1] row_mask:0xf bank_mask:0xf bound_ctrl:1
	s_nop 0
	ds_write_b32 v116, v157 offset:28672
	v_add_f32_dpp v151, v151, v151 row_half_mirror row_mask:0xf bank_mask:0xf bound_ctrl:1
	v_cvt_pkrtz_f16_f32 v152, -v151, -v151
	v_pk_mul_f16 v153, v152, v138
	v_pk_mul_f16 v154, v152, v139
	v_pk_mul_f16 v155, v152, v140
	v_pk_mul_f16 v156, v152, v141
	v_pk_fma_f16 v153, v160, v142, v153
	v_pk_fma_f16 v154, v160, v143, v154
	v_pk_fma_f16 v155, v160, v144, v155
	v_pk_fma_f16 v156, v160, v145, v156
	v_pk_fma_f16 v127, v127, v130, v153
	v_pk_fma_f16 v126, v126, v131, v154
	v_pk_fma_f16 v125, v125, v132, v155
	v_pk_fma_f16 v124, v124, v133, v156
	v_dot2_f32_f16 v158, v127, v146, 0
	v_dot2_f32_f16 v158, v126, v147, v158
	v_dot2_f32_f16 v158, v125, v148, v158
	v_dot2_f32_f16 v158, v124, v149, v158
	s_nop 2
	ds_write_b32 v116, v158 offset:30720
	s_xor_b32 s100, s100, 0xe100
	s_cmpk_lg_i32 s30, 0x80
	s_cbranch_scc0 .LBB0_1250
	s_mov_b32 s4, s30
	s_and_saveexec_b64 s[18:19], s[10:11]
	s_cbranch_execnz .LBB0_1229
	s_branch .LBB0_1230
.LBB0_1250:
	s_waitcnt lgkmcnt(0)
	s_barrier
	s_movk_i32 s98, 0x7f
	s_xor_b32 s101, s100, 0xe100
	s_cmp_lg_u32 s100, 0
	s_cselect_b32 s97, 0, 64
	v_add_u32_e32 v166, s97, v123
	s_waitcnt lgkmcnt(1)
	ds_read_b128 v[56:59], v94 offset:57856
	ds_read_b128 v[60:63], v94 offset:57872
	ds_read_b128 v[64:67], v94 offset:57888
	ds_read_b128 v[68:71], v94 offset:57904
	s_waitcnt lgkmcnt(3)
	v_add_f32_e32 v56, v56, v57
	v_add_f32_e32 v57, v58, v59
	v_add_f32_e32 v56, v56, v57
	s_waitcnt lgkmcnt(2)
	v_add_f32_e32 v57, v60, v61
	v_add_f32_e32 v58, v62, v63
	v_add_f32_e32 v57, v57, v58
	v_add_f32_e32 v56, v56, v57
	s_waitcnt lgkmcnt(1)
	v_add_f32_e32 v57, v64, v65
	v_add_f32_e32 v58, v66, v67
	v_add_f32_e32 v57, v57, v58
	s_waitcnt lgkmcnt(0)
	v_add_f32_e32 v58, v68, v69
	v_add_f32_e32 v59, v70, v71
	v_add_f32_e32 v58, v58, v59
	v_add_f32_e32 v57, v57, v58
	v_add_f32_e32 v58, v56, v57
	s_nop 1
	v_add_f32_dpp v58, v58, v58 quad_perm:[1,0,3,2] row_mask:0xf bank_mask:0xf bound_ctrl:1
	s_nop 1
	v_add_f32_dpp v58, v58, v58 quad_perm:[2,3,0,1] row_mask:0xf bank_mask:0xf bound_ctrl:1
	s_nop 1
	v_add_f32_dpp v58, v58, v58 row_half_mirror row_mask:0xf bank_mask:0xf bound_ctrl:1
	s_nop 1
	v_add_f32_dpp v58, v58, v58 row_mirror row_mask:0xf bank_mask:0xf bound_ctrl:1
	s_nop 0
	v_readlane_b32 s19, v58, 16
	v_readlane_b32 s23, v58, 48
	v_readlane_b32 s18, v58, 0
	v_readlane_b32 s22, v58, 32
	v_mov_b32_e32 v58, s19
	v_mov_b32_e32 v59, s23
	v_add_f32_e32 v58, s18, v58
	v_add_f32_e32 v59, s22, v59
	v_cndmask_b32_e64 v58, v59, v58, s[12:13]
	v_fmac_f32_e32 v57, 0xbc800000, v58
	v_fmac_f32_e32 v56, 0xbc800000, v58
	v_mul_f32_e32 v58, v57, v57
	v_fmac_f32_e32 v58, v56, v56
	s_nop 1
	v_add_f32_dpp v58, v58, v58 quad_perm:[1,0,3,2] row_mask:0xf bank_mask:0xf bound_ctrl:1
	s_nop 1
	v_add_f32_dpp v58, v58, v58 quad_perm:[2,3,0,1] row_mask:0xf bank_mask:0xf bound_ctrl:1
	s_nop 1
	v_add_f32_dpp v58, v58, v58 row_half_mirror row_mask:0xf bank_mask:0xf bound_ctrl:1
	s_nop 1
	v_add_f32_dpp v58, v58, v58 row_mirror row_mask:0xf bank_mask:0xf bound_ctrl:1
	s_nop 0
	v_readlane_b32 s22, v58, 0
	v_readlane_b32 s24, v58, 16
	v_readlane_b32 s23, v58, 32
	v_readlane_b32 s25, v58, 48
	s_and_saveexec_b64 s[18:19], s[16:17]
	s_cbranch_execz .Lrw_dend2
	v_mov_b32_e32 v58, s24
	v_mov_b32_e32 v59, s25
	v_add_f32_e32 v58, s22, v58
	v_add_f32_e32 v59, s23, v59
	v_cndmask_b32_e64 v58, v59, v58, s[12:13]
	v_fmamk_f32 v58, v58, 0x3c800000, v120
	v_mul_f32_e32 v59, 0x4b800000, v58
	v_cmp_gt_f32_e32 vcc, s29, v58
	s_nop 1
	v_cndmask_b32_e32 v58, v58, v59, vcc
	v_rsq_f32_e32 v60, v58
	v_add_u32_e32 v165, s101, v121
	v_mov_b32_e32 v58, v162
	v_mov_b32_e32 v59, v163
	ds_read_b32 v105, v166 offset:57600
	ds_read_b64 v[62:63], v165 offset:37120
	v_mul_f32_e32 v61, 0x45800000, v60
	v_cndmask_b32_e32 v64, v60, v61, vcc
	v_mul_f32_e32 v60, v57, v64
	s_waitcnt lgkmcnt(2)
	v_mov_b32_e32 v61, v59
	s_waitcnt lgkmcnt(1)
	v_pk_mul_f32 v[60:61], v[104:105], v[60:61]
	v_mul_f32_e32 v56, v56, v64
	v_add_f32_e32 v57, v87, v60
	v_add_f32_e32 v57, v57, v61
	s_waitcnt lgkmcnt(0)
	v_mul_f32_e32 v59, v63, v57
	v_mov_b32_e32 v85, v105
	v_mov_b32_e32 v57, v58
	v_pk_mul_f32 v[56:57], v[84:85], v[56:57]
	s_nop 0
	v_add_f32_e32 v56, v86, v56
	v_add_f32_e32 v56, v56, v57
	v_mul_f32_e32 v56, v62, v56
	v_cvt_pk_bf16_f32 v58, v56, v59
	v_lshl_add_u32 v56, s98, 4, v95
	v_ashrrev_i32_e32 v57, 31, v56
	v_lshlrev_b64 v[56:57], 12, v[56:57]
	v_lshl_add_u64 v[56:57], v[106:107], 0, v[56:57]
	global_store_dword v[56:57], v58, off offset:2048
